# MLA mixer tile loop: waves 4-7 take the per-tile barrier after the QK block (staggered halves), waves 0-3 at the tile end
# speedup vs baseline: 1.0057x; 1.0057x over previous
.LBB0_766:
	s_lshl_b32 s1, s14, 5
	s_and_b32 s0, s14, 0xffffff00
	s_and_b32 s1, s1, 0xe0
	s_or_b32 s0, s1, s0
	s_bfe_u32 s1, s14, 0x50003
	s_or_b32 s2, s0, s1
	v_readlane_b32 s0, v254, 15
	v_readlane_b32 s1, v254, 16
	s_and_b64 s[0:1], s[0:1], exec
	s_cselect_b32 s2, s2, s14
	s_bfe_u32 s12, s2, 0x20003
	s_ashr_i32 s16, s2, 5
	v_mov_b32_e32 v0, v185
	s_mov_b64 s[4:5], s[40:41]
	s_mul_i32 s0, s12, 0xc0
	s_add_u32 s0, s4, s0
	s_addc_u32 s1, s5, 0
	s_add_u32 s0, s0, 0x16e00000
	s_addc_u32 s1, s1, 0
	s_lshl_b32 s3, s12, 7
	s_add_u32 s3, s4, s3
	s_addc_u32 s7, s5, 0
	s_add_u32 s6, s3, 0x18900000
	s_addc_u32 s7, s7, 0
	v_mbcnt_lo_u32_b32 v0, -1, v0
	s_add_u32 s8, s4, 0xba01300
	v_mbcnt_hi_u32_b32 v22, -1, v0
	s_addc_u32 s9, s5, 0
	s_lshl_b32 s2, s2, 8
	v_and_b32_e32 v23, 31, v22
	s_lshl_b32 s15, s16, 11
	s_and_b32 s2, s2, 0x700
	v_readlane_b32 s3, v255, 6
	s_or_b32 s2, s2, s15
	v_bfe_u32 v24, v22, 5, 1
	v_or_b32_e32 v0, s3, v23
	v_add_u32_e32 v176, s2, v0
	v_mov_b64_e32 v[0:1], s[0:1]
	s_movk_i32 s0, 0x300
	v_mad_i64_i32 v[0:1], s[0:1], v176, s0, v[0:1]
	v_lshlrev_b32_e32 v184, 4, v24
	v_lshl_add_u64 v[0:1], v[0:1], 0, v[184:185]
	global_load_dwordx4 v[96:99], v[0:1], off
	global_load_dwordx4 v[100:103], v[0:1], off offset:32
	global_load_dwordx4 v[104:107], v[0:1], off offset:64
	global_load_dwordx4 v[108:111], v[0:1], off offset:96
	global_load_dwordx4 v[112:115], v[0:1], off offset:128
	global_load_dwordx4 v[116:119], v[0:1], off offset:160
	v_readlane_b32 s0, v252, 16
	s_nop 1
	v_add_u32_e32 v8, s0, v22
	s_mov_b32 s0, 0x2aaaaaab
	v_mul_hi_i32 v0, v8, s0
	v_lshrrev_b32_e32 v1, 31, v0
	v_ashrrev_i32_e32 v0, 1, v0
	v_add_u32_e32 v194, v0, v1
	v_mul_lo_u32 v0, v194, 12
	v_sub_u32_e32 v25, v8, v0
	v_add_u32_e32 v2, s15, v194
	v_cmp_lt_i32_e64 s[0:1], 7, v25
	v_ashrrev_i32_e32 v3, 31, v2
	v_lshlrev_b32_e32 v12, 3, v25
	s_and_saveexec_b64 s[2:3], s[0:1]
	s_xor_b64 s[2:3], exec, s[2:3]
	v_mov_b64_e32 v[0:1], s[8:9]
	v_mad_i64_i32 v[0:1], s[10:11], v2, s33, v[0:1]
	v_mov_b32_e32 v13, v185
	v_lshl_add_u64 v[0:1], v[12:13], 1, v[0:1]
	v_lshl_add_u64 v[0:1], v[0:1], 0, s[28:29]
	s_or_saveexec_b64 s[2:3], s[2:3]
	v_ashrrev_i32_e32 v26, 31, v12
	s_xor_b64 exec, exec, s[2:3]
	v_lshlrev_b64 v[0:1], 9, v[2:3]
	v_lshl_add_u64 v[0:1], s[6:7], 0, v[0:1]
	v_mov_b32_e32 v13, v26
	v_lshl_add_u64 v[0:1], v[12:13], 1, v[0:1]
	s_or_b64 exec, exec, s[2:3]
	global_load_dwordx4 v[0:3], v[0:1], off
	v_bitop3_b16 v4, v8, s26, v251 bitop3:0xec
	s_mov_b32 s2, 0xaaab
	v_mul_u32_u24_sdwa v5, v4, s2 dst_sel:DWORD dst_unused:UNUSED_PAD src0_sel:WORD_0 src1_sel:DWORD
	v_lshrrev_b32_e32 v195, 19, v5
	v_mul_lo_u16_e32 v5, 12, v195
	v_sub_u16_e32 v27, v4, v5
	v_or_b32_e32 v6, s15, v195
	v_lshlrev_b32_e32 v4, 3, v27
	v_cmp_lt_u16_e64 s[2:3], 7, v27
	v_ashrrev_i32_e32 v7, 31, v6
	v_lshlrev_b32_e32 v14, 1, v4
	s_and_saveexec_b64 s[10:11], s[2:3]
	s_xor_b64 s[10:11], exec, s[10:11]
	v_mov_b64_e32 v[4:5], s[8:9]
	v_mad_i64_i32 v[4:5], s[18:19], v6, s33, v[4:5]
	v_mov_b32_e32 v15, v185
	v_lshl_add_u64 v[4:5], v[4:5], 0, v[14:15]
	v_lshl_add_u64 v[4:5], v[4:5], 0, s[28:29]
	s_andn2_saveexec_b64 s[10:11], s[10:11]
	v_lshlrev_b64 v[4:5], 9, v[6:7]
	v_lshl_add_u64 v[4:5], s[6:7], 0, v[4:5]
	v_mov_b32_e32 v15, v185
	v_lshl_add_u64 v[4:5], v[4:5], 0, v[14:15]
	s_or_b64 exec, exec, s[10:11]
	s_lshl_b32 s10, s12, 6
	s_lshl_b32 s60, s10, 1
	s_add_u32 s10, s4, s60
	v_ashrrev_i32_e32 v196, 3, v8
	s_addc_u32 s11, s5, 0
	v_add_u32_e32 v8, s15, v196
	s_add_u32 s10, s10, 0x19b00000
	v_ashrrev_i32_e32 v9, 31, v8
	s_addc_u32 s11, s11, 0
	v_and_b32_e32 v28, 7, v22
	v_lshlrev_b64 v[8:9], 9, v[8:9]
	v_lshl_add_u64 v[8:9], s[10:11], 0, v[8:9]
	v_lshlrev_b32_e32 v16, 4, v28
	v_mov_b32_e32 v17, v185
	v_lshl_add_u64 v[8:9], v[8:9], 0, v[16:17]
	global_load_dwordx4 v[4:7], v[4:5], off
	s_or_b32 s17, s15, 64
	global_load_dwordx4 v[8:11], v[8:9], off
	v_add_u32_e32 v20, s17, v194
	v_ashrrev_i32_e32 v21, 31, v20
	s_and_saveexec_b64 s[12:13], s[0:1]
	s_xor_b64 s[12:13], exec, s[12:13]
	v_mov_b64_e32 v[18:19], s[8:9]
	v_mad_i64_i32 v[18:19], s[18:19], v20, s33, v[18:19]
	v_mov_b32_e32 v13, v185
	v_lshl_add_u64 v[18:19], v[12:13], 1, v[18:19]
	v_lshl_add_u64 v[18:19], v[18:19], 0, s[28:29]
	s_andn2_saveexec_b64 s[12:13], s[12:13]
	v_lshlrev_b64 v[18:19], 9, v[20:21]
	v_lshl_add_u64 v[18:19], s[6:7], 0, v[18:19]
	v_mov_b32_e32 v13, v26
	v_lshl_add_u64 v[18:19], v[12:13], 1, v[18:19]
	s_or_b64 exec, exec, s[12:13]
	global_load_dwordx4 v[120:123], v[18:19], off
	v_or_b32_e32 v20, s17, v195
	v_ashrrev_i32_e32 v21, 31, v20
	s_and_saveexec_b64 s[12:13], s[2:3]
	s_xor_b64 s[12:13], exec, s[12:13]
	v_mov_b64_e32 v[18:19], s[8:9]
	v_mad_i64_i32 v[18:19], s[18:19], v20, s33, v[18:19]
	v_mov_b32_e32 v15, v185
	v_lshl_add_u64 v[18:19], v[18:19], 0, v[14:15]
	v_lshl_add_u64 v[18:19], v[18:19], 0, s[28:29]
	s_andn2_saveexec_b64 s[12:13], s[12:13]
	v_lshlrev_b64 v[18:19], 9, v[20:21]
	v_lshl_add_u64 v[18:19], s[6:7], 0, v[18:19]
	v_mov_b32_e32 v15, v185
	v_lshl_add_u64 v[18:19], v[18:19], 0, v[14:15]
	s_or_b64 exec, exec, s[12:13]
	global_load_dwordx4 v[124:127], v[18:19], off
	v_add_u32_e32 v18, s17, v196
	v_ashrrev_i32_e32 v19, 31, v18
	v_lshlrev_b32_e32 v13, 3, v28
	v_lshlrev_b64 v[18:19], 9, v[18:19]
	v_lshl_add_u64 v[18:19], s[10:11], 0, v[18:19]
	v_lshlrev_b32_e32 v20, 1, v13
	v_mov_b32_e32 v21, v185
	v_lshl_add_u64 v[18:19], v[18:19], 0, v[20:21]
	global_load_dwordx4 v[128:131], v[18:19], off
	v_mul_lo_u32 v13, v194, s81
	v_add_u32_e32 v13, 0, v13
	v_lshlrev_b32_e32 v15, 4, v25
	v_add_u32_e32 v198, v13, v15
	s_waitcnt vmcnt(5)
	ds_write_b128 v198, v[0:3]
	v_mad_u32_u24 v0, v195, s81, 0
	v_lshlrev_b32_e32 v1, 4, v27
	v_add_u32_e32 v199, v0, v1
	v_mul_lo_u32 v0, v196, s80
	v_add_u32_e32 v0, 0, v0
	v_add_u32_e32 v200, v0, v16
	v_bfe_u32 v0, v22, 2, 2
	v_lshl_or_b32 v0, v24, 2, v0
	s_waitcnt vmcnt(4)
	ds_write_b128 v199, v[4:7]
	s_waitcnt vmcnt(3)
	ds_write_b128 v200, v[8:11] offset:26624
	v_mad_u32_u24 v33, v0, s80, 0
	v_and_b32_e32 v0, 16, v22
	v_lshlrev_b32_e32 v1, 2, v23
	s_waitcnt lgkmcnt(0)
	s_barrier
	v_and_or_b32 v0, v1, 12, v0
	v_mov_b32_e32 v13, v185
	s_lshl_b32 s12, s16, 8
	v_mad_u32_u24 v32, v23, s81, 0
	v_lshlrev_b32_e32 v34, 1, v0
	v_lshl_add_u64 v[180:181], v[12:13], 1, s[8:9]
	v_mov_b32_e32 v13, v26
	v_mov_b32_e32 v15, v185
	v_mov_b32_e32 v203, 0
	v_ashrrev_i32_e32 v177, 31, v176
	v_lshlrev_b32_e32 v197, 3, v24
	s_add_i32 s12, s12, 0x8000
	v_lshl_add_u64 v[178:179], s[10:11], 0, v[20:21]
	v_lshl_add_u64 v[182:183], v[12:13], 1, s[6:7]
	v_lshl_add_u64 v[190:191], s[8:9], 0, v[14:15]
	v_lshl_add_u64 v[192:193], s[6:7], 0, v[14:15]
	s_mov_b32 s13, 0
	v_mov_b32_e32 v16, v185
	v_mov_b32_e32 v17, v185
	v_mov_b32_e32 v18, v185
	v_mov_b32_e32 v19, v185
	v_mov_b32_e32 v20, v185
	v_mov_b32_e32 v22, v185
	v_mov_b32_e32 v23, v185
	v_mov_b32_e32 v24, v185
	v_mov_b32_e32 v25, v185
	v_mov_b32_e32 v26, v185
	v_mov_b32_e32 v27, v185
	v_mov_b32_e32 v28, v185
	v_mov_b32_e32 v29, v185
	v_mov_b32_e32 v30, v185
	v_mov_b32_e32 v31, v185
	v_mov_b32_e32 v0, v185
	v_mov_b32_e32 v1, v185
	v_mov_b32_e32 v2, v185
	v_mov_b32_e32 v3, v185
	v_mov_b32_e32 v4, v185
	v_mov_b32_e32 v5, v185
	v_mov_b32_e32 v6, v185
	v_mov_b32_e32 v7, v185
	v_mov_b32_e32 v8, v185
	v_mov_b32_e32 v9, v185
	v_mov_b32_e32 v10, v185
	v_mov_b32_e32 v11, v185
	v_mov_b32_e32 v12, v185
	v_mov_b32_e32 v13, v185
	v_mov_b32_e32 v14, v185
	v_add_u32_e32 v184, v32, v184
	v_add_u32_e32 v201, v33, v34
	v_mov_b32_e32 v202, 0
	v_mov_b32_e32 v32, 0
	v_mov_b32_e32 v33, v203
	v_mov_b32_e32 v34, v203
	v_mov_b32_e32 v35, v203
	v_mov_b32_e32 v36, v203
	v_mov_b32_e32 v37, v203
	v_mov_b32_e32 v38, v203
	v_mov_b32_e32 v39, v203
	v_mov_b32_e32 v40, v203
	v_mov_b32_e32 v41, v203
	v_mov_b32_e32 v42, v203
	v_mov_b32_e32 v43, v203
	v_mov_b32_e32 v44, v203
	v_mov_b32_e32 v45, v203
	v_mov_b32_e32 v46, v203
	v_mov_b32_e32 v47, v203
	v_readlane_b32 s99, v255, 23
.LBB0_783:
	ds_read_b128 v[48:51], v184 offset:0
	ds_read_b128 v[52:55], v184 offset:32
	ds_read_b128 v[56:59], v184 offset:64
	ds_read_b128 v[60:63], v184 offset:96
	ds_read_b128 v[64:67], v184 offset:128
	ds_read_b128 v[68:71], v184 offset:160
	ds_read_b128 v[72:75], v184 offset:6656
	ds_read_b128 v[76:79], v184 offset:6688
	ds_read_b128 v[80:83], v184 offset:6720
	ds_read_b128 v[84:87], v184 offset:6752
	ds_read_b128 v[88:91], v184 offset:6784
	ds_read_b128 v[92:95], v184 offset:6816
	s_add_i32 s16, s13, 2
	s_min_u32 s6, s16, 35
	s_cmp_lt_u32 s13, 30
	s_cselect_b32 s7, 0, 0xffffffe0
	s_cselect_b32 s8, s15, s12
	s_add_i32 s7, s7, s6
	s_lshl_b32 s6, s7, 6
	s_add_i32 s8, s6, s8
	v_add_u32_e32 v208, s8, v194
	v_ashrrev_i32_e32 v209, 31, v208
	s_and_saveexec_b64 s[6:7], s[0:1]
	s_xor_b64 s[6:7], exec, s[6:7]
	v_mad_i64_i32 v[206:207], s[10:11], v208, s33, v[180:181]
	v_lshl_add_u64 v[206:207], v[206:207], 0, s[28:29]
	s_andn2_saveexec_b64 s[6:7], s[6:7]
	v_lshlrev_b64 v[206:207], 9, v[208:209]
	v_lshl_add_u64 v[206:207], v[182:183], 0, v[206:207]
	s_or_b64 exec, exec, s[6:7]
	global_load_dwordx4 v[132:135], v[206:207], off
	v_or_b32_e32 v208, s8, v195
	v_ashrrev_i32_e32 v209, 31, v208
	s_and_saveexec_b64 s[6:7], s[2:3]
	s_xor_b64 s[6:7], exec, s[6:7]
	v_mad_i64_i32 v[206:207], s[10:11], v208, s33, v[190:191]
	v_lshl_add_u64 v[206:207], v[206:207], 0, s[28:29]
	s_andn2_saveexec_b64 s[6:7], s[6:7]
	v_lshlrev_b64 v[206:207], 9, v[208:209]
	v_lshl_add_u64 v[206:207], v[192:193], 0, v[206:207]
	s_or_b64 exec, exec, s[6:7]
	global_load_dwordx4 v[136:139], v[206:207], off
	v_add_u32_e32 v206, s8, v196
	v_ashrrev_i32_e32 v207, 31, v206
	v_lshlrev_b64 v[206:207], 9, v[206:207]
	v_lshl_add_u64 v[206:207], v[178:179], 0, v[206:207]
	global_load_dwordx4 v[140:143], v[206:207], off
	s_waitcnt lgkmcnt(11)
	v_mfma_f32_32x32x16_bf16 v[144:159], v[48:51], v[96:99], v[32:47]
	s_waitcnt lgkmcnt(10)
	v_mfma_f32_32x32x16_bf16 v[144:159], v[52:55], v[100:103], v[144:159]
	s_waitcnt lgkmcnt(9)
	v_mfma_f32_32x32x16_bf16 v[144:159], v[56:59], v[104:107], v[144:159]
	s_waitcnt lgkmcnt(8)
	v_mfma_f32_32x32x16_bf16 v[144:159], v[60:63], v[108:111], v[144:159]
	s_waitcnt lgkmcnt(7)
	v_mfma_f32_32x32x16_bf16 v[144:159], v[64:67], v[112:115], v[144:159]
	s_waitcnt lgkmcnt(6)
	v_mfma_f32_32x32x16_bf16 v[144:159], v[68:71], v[116:119], v[144:159]
	s_waitcnt lgkmcnt(5)
	v_mfma_f32_32x32x16_bf16 v[160:175], v[72:75], v[96:99], v[32:47]
	s_waitcnt lgkmcnt(4)
	v_mfma_f32_32x32x16_bf16 v[160:175], v[76:79], v[100:103], v[160:175]
	s_waitcnt lgkmcnt(3)
	v_mfma_f32_32x32x16_bf16 v[160:175], v[80:83], v[104:107], v[160:175]
	s_waitcnt lgkmcnt(2)
	v_mfma_f32_32x32x16_bf16 v[160:175], v[84:87], v[108:111], v[160:175]
	s_waitcnt lgkmcnt(1)
	v_mfma_f32_32x32x16_bf16 v[160:175], v[88:91], v[112:115], v[160:175]
	s_waitcnt lgkmcnt(0)
	v_mfma_f32_32x32x16_bf16 v[160:175], v[92:95], v[116:119], v[160:175]
	ds_read_b64_tr_b16 v[48:49], v201 offset:26624
	ds_read_b64_tr_b16 v[50:51], v201 offset:28160
	ds_read_b64_tr_b16 v[52:53], v201 offset:26688
	ds_read_b64_tr_b16 v[54:55], v201 offset:28224
	ds_read_b64_tr_b16 v[56:57], v201 offset:29696
	ds_read_b64_tr_b16 v[58:59], v201 offset:31232
	ds_read_b64_tr_b16 v[60:61], v201 offset:29760
	ds_read_b64_tr_b16 v[62:63], v201 offset:31296
	ds_read_b64_tr_b16 v[64:65], v201 offset:32768
	ds_read_b64_tr_b16 v[66:67], v201 offset:34304
	ds_read_b64_tr_b16 v[68:69], v201 offset:32832
	ds_read_b64_tr_b16 v[70:71], v201 offset:34368
	ds_read_b64_tr_b16 v[72:73], v201 offset:35840
	ds_read_b64_tr_b16 v[74:75], v201 offset:37376
	ds_read_b64_tr_b16 v[76:77], v201 offset:35904
	ds_read_b64_tr_b16 v[78:79], v201 offset:37440
	s_cmp_eq_u32 s99, 0
	s_cbranch_scc0 .Lm1_xA
	s_waitcnt vmcnt(5)
	ds_write_b128 v198, v[120:123] offset:13312
	s_waitcnt vmcnt(4)
	ds_write_b128 v199, v[124:127] offset:13312
	s_waitcnt vmcnt(3)
	ds_write_b128 v200, v[128:131] offset:38912
	s_waitcnt lgkmcnt(0)
	s_barrier
.Lm1_xA:
	v_exp_f32_e32 v144, v144
	v_exp_f32_e32 v145, v145
	v_exp_f32_e32 v146, v146
	v_exp_f32_e32 v147, v147
	v_exp_f32_e32 v148, v148
	v_exp_f32_e32 v149, v149
	v_exp_f32_e32 v150, v150
	v_exp_f32_e32 v151, v151
	v_add_f32_e32 v204, v144, v146
	v_add_f32_e32 v205, v145, v147
	v_add_f32_e32 v204, v204, v148
	v_add_f32_e32 v205, v205, v149
	v_add_f32_e32 v204, v204, v150
	v_add_f32_e32 v205, v205, v151
	v_cvt_pk_bf16_f32 v144, v144, v145
	v_cvt_pk_bf16_f32 v145, v146, v147
	v_cvt_pk_bf16_f32 v146, v148, v149
	v_cvt_pk_bf16_f32 v147, v150, v151
	v_exp_f32_e32 v152, v152
	v_exp_f32_e32 v153, v153
	s_waitcnt lgkmcnt(14)
	v_mfma_f32_32x32x16_bf16 v[16:31], v[48:51], v[144:147], v[16:31]
	v_exp_f32_e32 v154, v154
	v_exp_f32_e32 v155, v155
	v_exp_f32_e32 v156, v156
	s_waitcnt lgkmcnt(12)
	v_mfma_f32_32x32x16_bf16 v[0:15], v[52:55], v[144:147], v[0:15]
	v_exp_f32_e32 v157, v157
	v_exp_f32_e32 v158, v158
	v_exp_f32_e32 v159, v159
	v_add_f32_e32 v204, v204, v152
	v_add_f32_e32 v205, v205, v153
	v_add_f32_e32 v204, v204, v154
	v_add_f32_e32 v205, v205, v155
	v_add_f32_e32 v204, v204, v156
	v_add_f32_e32 v205, v205, v157
	v_add_f32_e32 v204, v204, v158
	v_add_f32_e32 v205, v205, v159
	v_cvt_pk_bf16_f32 v152, v152, v153
	v_cvt_pk_bf16_f32 v153, v154, v155
	v_cvt_pk_bf16_f32 v154, v156, v157
	v_cvt_pk_bf16_f32 v155, v158, v159
	v_exp_f32_e32 v160, v160
	v_exp_f32_e32 v161, v161
	s_waitcnt lgkmcnt(10)
	v_mfma_f32_32x32x16_bf16 v[16:31], v[56:59], v[152:155], v[16:31]
	v_exp_f32_e32 v162, v162
	v_exp_f32_e32 v163, v163
	v_exp_f32_e32 v164, v164
	s_waitcnt lgkmcnt(8)
	v_mfma_f32_32x32x16_bf16 v[0:15], v[60:63], v[152:155], v[0:15]
	v_exp_f32_e32 v165, v165
	v_exp_f32_e32 v166, v166
	v_exp_f32_e32 v167, v167
	v_add_f32_e32 v204, v204, v160
	v_add_f32_e32 v205, v205, v161
	v_add_f32_e32 v204, v204, v162
	v_add_f32_e32 v205, v205, v163
	v_add_f32_e32 v204, v204, v164
	v_add_f32_e32 v205, v205, v165
	v_add_f32_e32 v204, v204, v166
	v_add_f32_e32 v205, v205, v167
	v_cvt_pk_bf16_f32 v160, v160, v161
	v_cvt_pk_bf16_f32 v161, v162, v163
	v_cvt_pk_bf16_f32 v162, v164, v165
	v_cvt_pk_bf16_f32 v163, v166, v167
	v_exp_f32_e32 v168, v168
	v_exp_f32_e32 v169, v169
	s_waitcnt lgkmcnt(6)
	v_mfma_f32_32x32x16_bf16 v[16:31], v[64:67], v[160:163], v[16:31]
	v_exp_f32_e32 v170, v170
	v_exp_f32_e32 v171, v171
	v_exp_f32_e32 v172, v172
	s_waitcnt lgkmcnt(4)
	v_mfma_f32_32x32x16_bf16 v[0:15], v[68:71], v[160:163], v[0:15]
	v_exp_f32_e32 v173, v173
	v_exp_f32_e32 v174, v174
	v_exp_f32_e32 v175, v175
	v_add_f32_e32 v204, v204, v168
	v_add_f32_e32 v205, v205, v169
	v_add_f32_e32 v204, v204, v170
	v_add_f32_e32 v205, v205, v171
	v_add_f32_e32 v204, v204, v172
	v_add_f32_e32 v205, v205, v173
	v_add_f32_e32 v204, v204, v174
	v_add_f32_e32 v205, v205, v175
	v_cvt_pk_bf16_f32 v168, v168, v169
	v_cvt_pk_bf16_f32 v169, v170, v171
	v_cvt_pk_bf16_f32 v170, v172, v173
	v_cvt_pk_bf16_f32 v171, v174, v175
	s_nop 1
	s_waitcnt lgkmcnt(2)
	v_mfma_f32_32x32x16_bf16 v[16:31], v[72:75], v[168:171], v[16:31]
	s_waitcnt lgkmcnt(0)
	v_mfma_f32_32x32x16_bf16 v[0:15], v[76:79], v[168:171], v[0:15]
	s_cmp_eq_u32 s99, 0
	s_cbranch_scc1 .Lm1_yA
	s_waitcnt vmcnt(5)
	ds_write_b128 v198, v[120:123] offset:13312
	s_waitcnt vmcnt(4)
	ds_write_b128 v199, v[124:127] offset:13312
	s_waitcnt vmcnt(3)
	ds_write_b128 v200, v[128:131] offset:38912
.Lm1_yA:
	v_add_f32_e32 v204, v204, v205
	v_add_f32_e32 v203, v203, v204
	s_mov_b32 s6, 0x43800000
	s_cmp_eq_u32 s13, 0
	s_cselect_b32 s6, 0xbf800000, s6
	s_cbranch_scc1 .Lm1_rareA
	v_cmp_lt_f32_e32 vcc, 0x43000000, v204
	s_cbranch_vccz .Lm1_noresA

.Lm1_noresA:
	s_cmp_eq_u32 s99, 0
	s_cbranch_scc1 .Lm1_zA
	s_waitcnt lgkmcnt(0)
	s_barrier
.Lm1_zA:
	ds_read_b128 v[48:51], v184 offset:13312
	ds_read_b128 v[52:55], v184 offset:13344
	ds_read_b128 v[56:59], v184 offset:13376
	ds_read_b128 v[60:63], v184 offset:13408
	ds_read_b128 v[64:67], v184 offset:13440
	ds_read_b128 v[68:71], v184 offset:13472
	ds_read_b128 v[72:75], v184 offset:19968
	ds_read_b128 v[76:79], v184 offset:20000
	ds_read_b128 v[80:83], v184 offset:20032
	ds_read_b128 v[84:87], v184 offset:20064
	ds_read_b128 v[88:91], v184 offset:20096
	ds_read_b128 v[92:95], v184 offset:20128
	s_min_u32 s6, s13, 32
	s_cmp_lt_u32 s13, 29
	s_cselect_b32 s7, 0, 0xffffffe0
	s_cselect_b32 s8, s15, s12
	s_add_i32 s6, s6, s7
	s_lshl_b32 s6, s6, 6
	s_add_i32 s8, s6, s8
	s_addk_i32 s8, 0xc0
	v_add_u32_e32 v208, s8, v194
	v_ashrrev_i32_e32 v209, 31, v208
	s_and_saveexec_b64 s[6:7], s[0:1]
	s_xor_b64 s[6:7], exec, s[6:7]
	v_mad_i64_i32 v[206:207], s[10:11], v208, s33, v[180:181]
	v_lshl_add_u64 v[206:207], v[206:207], 0, s[28:29]
	s_andn2_saveexec_b64 s[6:7], s[6:7]
	v_lshlrev_b64 v[206:207], 9, v[208:209]
	v_lshl_add_u64 v[206:207], v[182:183], 0, v[206:207]
	s_or_b64 exec, exec, s[6:7]
	global_load_dwordx4 v[120:123], v[206:207], off
	v_or_b32_e32 v208, s8, v195
	v_ashrrev_i32_e32 v209, 31, v208
	s_and_saveexec_b64 s[6:7], s[2:3]
	s_xor_b64 s[6:7], exec, s[6:7]
	v_mad_i64_i32 v[206:207], s[10:11], v208, s33, v[190:191]
	v_lshl_add_u64 v[206:207], v[206:207], 0, s[28:29]
	s_andn2_saveexec_b64 s[6:7], s[6:7]
	v_lshlrev_b64 v[206:207], 9, v[208:209]
	v_lshl_add_u64 v[206:207], v[192:193], 0, v[206:207]
	s_or_b64 exec, exec, s[6:7]
	global_load_dwordx4 v[124:127], v[206:207], off
	v_add_u32_e32 v206, s8, v196
	v_ashrrev_i32_e32 v207, 31, v206
	v_lshlrev_b64 v[206:207], 9, v[206:207]
	v_lshl_add_u64 v[206:207], v[178:179], 0, v[206:207]
	global_load_dwordx4 v[128:131], v[206:207], off
	s_waitcnt lgkmcnt(11)
	v_mfma_f32_32x32x16_bf16 v[144:159], v[48:51], v[96:99], v[32:47]
	s_waitcnt lgkmcnt(10)
	v_mfma_f32_32x32x16_bf16 v[144:159], v[52:55], v[100:103], v[144:159]
	s_waitcnt lgkmcnt(9)
	v_mfma_f32_32x32x16_bf16 v[144:159], v[56:59], v[104:107], v[144:159]
	s_waitcnt lgkmcnt(8)
	v_mfma_f32_32x32x16_bf16 v[144:159], v[60:63], v[108:111], v[144:159]
	s_waitcnt lgkmcnt(7)
	v_mfma_f32_32x32x16_bf16 v[144:159], v[64:67], v[112:115], v[144:159]
	s_waitcnt lgkmcnt(6)
	v_mfma_f32_32x32x16_bf16 v[144:159], v[68:71], v[116:119], v[144:159]
	s_waitcnt lgkmcnt(5)
	v_mfma_f32_32x32x16_bf16 v[160:175], v[72:75], v[96:99], v[32:47]
	s_waitcnt lgkmcnt(4)
	v_mfma_f32_32x32x16_bf16 v[160:175], v[76:79], v[100:103], v[160:175]
	s_waitcnt lgkmcnt(3)
	v_mfma_f32_32x32x16_bf16 v[160:175], v[80:83], v[104:107], v[160:175]
	s_waitcnt lgkmcnt(2)
	v_mfma_f32_32x32x16_bf16 v[160:175], v[84:87], v[108:111], v[160:175]
	s_waitcnt lgkmcnt(1)
	v_mfma_f32_32x32x16_bf16 v[160:175], v[88:91], v[112:115], v[160:175]
	s_waitcnt lgkmcnt(0)
	v_mfma_f32_32x32x16_bf16 v[160:175], v[92:95], v[116:119], v[160:175]
	ds_read_b64_tr_b16 v[48:49], v201 offset:38912
	ds_read_b64_tr_b16 v[50:51], v201 offset:40448
	ds_read_b64_tr_b16 v[52:53], v201 offset:38976
	ds_read_b64_tr_b16 v[54:55], v201 offset:40512
	ds_read_b64_tr_b16 v[56:57], v201 offset:41984
	ds_read_b64_tr_b16 v[58:59], v201 offset:43520
	ds_read_b64_tr_b16 v[60:61], v201 offset:42048
	ds_read_b64_tr_b16 v[62:63], v201 offset:43584
	ds_read_b64_tr_b16 v[64:65], v201 offset:45056
	ds_read_b64_tr_b16 v[66:67], v201 offset:46592
	ds_read_b64_tr_b16 v[68:69], v201 offset:45120
	ds_read_b64_tr_b16 v[70:71], v201 offset:46656
	ds_read_b64_tr_b16 v[72:73], v201 offset:48128
	ds_read_b64_tr_b16 v[74:75], v201 offset:49664
	ds_read_b64_tr_b16 v[76:77], v201 offset:48192
	ds_read_b64_tr_b16 v[78:79], v201 offset:49728
	s_cmp_eq_u32 s99, 0
	s_cbranch_scc0 .Lm1_xB
	s_cmp_gt_u32 s13, 33
	s_cbranch_scc1 .Lm1_skipwx
	s_waitcnt vmcnt(5)
	ds_write_b128 v198, v[132:135]
	s_waitcnt vmcnt(4)
	ds_write_b128 v199, v[136:139]
	s_waitcnt vmcnt(3)
	ds_write_b128 v200, v[140:143] offset:26624

.Lm1_xB:
	v_exp_f32_e32 v144, v144
	v_exp_f32_e32 v145, v145
	v_exp_f32_e32 v146, v146
	v_exp_f32_e32 v147, v147
	v_exp_f32_e32 v148, v148
	v_exp_f32_e32 v149, v149
	v_exp_f32_e32 v150, v150
	v_exp_f32_e32 v151, v151
	v_add_f32_e32 v204, v144, v146
	v_add_f32_e32 v205, v145, v147
	v_add_f32_e32 v204, v204, v148
	v_add_f32_e32 v205, v205, v149
	v_add_f32_e32 v204, v204, v150
	v_add_f32_e32 v205, v205, v151
	v_cvt_pk_bf16_f32 v144, v144, v145
	v_cvt_pk_bf16_f32 v145, v146, v147
	v_cvt_pk_bf16_f32 v146, v148, v149
	v_cvt_pk_bf16_f32 v147, v150, v151
	v_exp_f32_e32 v152, v152
	v_exp_f32_e32 v153, v153
	s_waitcnt lgkmcnt(14)
	v_mfma_f32_32x32x16_bf16 v[16:31], v[48:51], v[144:147], v[16:31]
	v_exp_f32_e32 v154, v154
	v_exp_f32_e32 v155, v155
	v_exp_f32_e32 v156, v156
	s_waitcnt lgkmcnt(12)
	v_mfma_f32_32x32x16_bf16 v[0:15], v[52:55], v[144:147], v[0:15]
	v_exp_f32_e32 v157, v157
	v_exp_f32_e32 v158, v158
	v_exp_f32_e32 v159, v159
	v_add_f32_e32 v204, v204, v152
	v_add_f32_e32 v205, v205, v153
	v_add_f32_e32 v204, v204, v154
	v_add_f32_e32 v205, v205, v155
	v_add_f32_e32 v204, v204, v156
	v_add_f32_e32 v205, v205, v157
	v_add_f32_e32 v204, v204, v158
	v_add_f32_e32 v205, v205, v159
	v_cvt_pk_bf16_f32 v152, v152, v153
	v_cvt_pk_bf16_f32 v153, v154, v155
	v_cvt_pk_bf16_f32 v154, v156, v157
	v_cvt_pk_bf16_f32 v155, v158, v159
	v_exp_f32_e32 v160, v160
	v_exp_f32_e32 v161, v161
	s_waitcnt lgkmcnt(10)
	v_mfma_f32_32x32x16_bf16 v[16:31], v[56:59], v[152:155], v[16:31]
	v_exp_f32_e32 v162, v162
	v_exp_f32_e32 v163, v163
	v_exp_f32_e32 v164, v164
	s_waitcnt lgkmcnt(8)
	v_mfma_f32_32x32x16_bf16 v[0:15], v[60:63], v[152:155], v[0:15]
	v_exp_f32_e32 v165, v165
	v_exp_f32_e32 v166, v166
	v_exp_f32_e32 v167, v167
	v_add_f32_e32 v204, v204, v160
	v_add_f32_e32 v205, v205, v161
	v_add_f32_e32 v204, v204, v162
	v_add_f32_e32 v205, v205, v163
	v_add_f32_e32 v204, v204, v164
	v_add_f32_e32 v205, v205, v165
	v_add_f32_e32 v204, v204, v166
	v_add_f32_e32 v205, v205, v167
	v_cvt_pk_bf16_f32 v160, v160, v161
	v_cvt_pk_bf16_f32 v161, v162, v163
	v_cvt_pk_bf16_f32 v162, v164, v165
	v_cvt_pk_bf16_f32 v163, v166, v167
	v_exp_f32_e32 v168, v168
	v_exp_f32_e32 v169, v169
	s_waitcnt lgkmcnt(6)
	v_mfma_f32_32x32x16_bf16 v[16:31], v[64:67], v[160:163], v[16:31]
	v_exp_f32_e32 v170, v170
	v_exp_f32_e32 v171, v171
	v_exp_f32_e32 v172, v172
	s_waitcnt lgkmcnt(4)
	v_mfma_f32_32x32x16_bf16 v[0:15], v[68:71], v[160:163], v[0:15]
	v_exp_f32_e32 v173, v173
	v_exp_f32_e32 v174, v174
	v_exp_f32_e32 v175, v175
	v_add_f32_e32 v204, v204, v168
	v_add_f32_e32 v205, v205, v169
	v_add_f32_e32 v204, v204, v170
	v_add_f32_e32 v205, v205, v171
	v_add_f32_e32 v204, v204, v172
	v_add_f32_e32 v205, v205, v173
	v_add_f32_e32 v204, v204, v174
	v_add_f32_e32 v205, v205, v175
	v_cvt_pk_bf16_f32 v168, v168, v169
	v_cvt_pk_bf16_f32 v169, v170, v171
	v_cvt_pk_bf16_f32 v170, v172, v173
	v_cvt_pk_bf16_f32 v171, v174, v175
	s_nop 1
	s_waitcnt lgkmcnt(2)
	v_mfma_f32_32x32x16_bf16 v[16:31], v[72:75], v[168:171], v[16:31]
	s_waitcnt lgkmcnt(0)
	v_mfma_f32_32x32x16_bf16 v[0:15], v[76:79], v[168:171], v[0:15]
	s_cmp_eq_u32 s99, 0
	s_cbranch_scc1 .Lm1_yB
	s_cmp_gt_u32 s13, 33
	s_cbranch_scc1 .Lm1_skipwy
	s_waitcnt vmcnt(5)
	ds_write_b128 v198, v[132:135]
	s_waitcnt vmcnt(4)
	ds_write_b128 v199, v[136:139]
	s_waitcnt vmcnt(3)
	ds_write_b128 v200, v[140:143] offset:26624
.Lm1_skipwy:
.Lm1_yB:
	v_add_f32_e32 v204, v204, v205
	v_add_f32_e32 v203, v203, v204
	s_mov_b32 s6, 0x43800000
	v_cmp_lt_f32_e32 vcc, 0x43000000, v204
	s_cbranch_vccz .Lm1_noresB

.Lm1_zB:
	s_cmp_gt_u32 s13, 33
	s_cbranch_scc1 .LBB0_765
	s_add_i32 s13, s13, 2
	s_branch .LBB0_783
